# grid barrier release flattened: non-leader workgroups poll the cross-XCC generation word directly instead of waiting for their XCC leader's relay
# baseline (speedup 1.0000x reference)
; DI unsigned xb_ld(unsigned* p)              { return __hip_atomic_load(p, __ATOMIC_RELAXED, __HIP_MEMORY_SCOPE_AGENT); }
; DI unsigned xb_add(unsigned* p, unsigned v) { return __hip_atomic_fetch_add(p, v, __ATOMIC_RELAXED, __HIP_MEMORY_SCOPE_AGENT); }
; #define XB_SPIN(cond, bar) do { unsigned _sp = 0; while (cond) { __builtin_amdgcn_s_sleep(1); \
;     if ((++_sp & 255u) == 0u) { if (xb_ld(&(bar)[XB_TMO])) break; if (_sp > XB_SPIN_CAP) { atomicAdd(&(bar)[XB_TMO], 1u); break; } } } } while (0)
; DI void xcd_barrier(const XcdBarrier& b) {
;     ...
;     const unsigned old = xb_add(&bar[XB_XSUB(b.x)], 1u);
;     const unsigned gen = old / nloc;
;     if (old + 1u == (gen + 1u) * nloc) {
;       __builtin_amdgcn_fence(__ATOMIC_RELEASE, "agent");
;       asm volatile("s_waitcnt vmcnt(0)" ::: "memory");
;       const unsigned og = xb_add(&bar[XB_TOP], 1u);
;       const unsigned tg = og / nx;
;       if (og + 1u == (tg + 1u) * nx) xb_add(&bar[XB_TOPGEN], 1u);
;       else XB_SPIN(xb_ld(&bar[XB_TOPGEN]) == tg, bar);
;       __builtin_amdgcn_fence(__ATOMIC_ACQUIRE, "agent");
;       xb_add(&bar[XB_XGEN(b.x)], 1u);
;       asm volatile("s_waitcnt vmcnt(0)" ::: "memory");
;     } else {
;       XB_SPIN(xb_ld(&bar[XB_XGEN(b.x)]) == gen, bar);
.LBB0_829:
	s_or_b64 exec, exec, s[4:5]
	v_cvt_f32_u32_e32 v5, v3
	s_waitcnt vmcnt(0)
	v_readfirstlane_b32 s4, v4
	v_sub_u32_e32 v4, 0, v3
	v_rcp_iflag_f32_e32 v5, v5
	v_add_u32_e32 v6, s4, v0
	v_mul_f32_e32 v5, 0x4f7ffffe, v5
	v_cvt_u32_f32_e32 v5, v5
	v_mul_lo_u32 v0, v4, v5
	v_mul_hi_u32 v0, v5, v0
	v_add_u32_e32 v0, v5, v0
	v_mul_hi_u32 v0, v6, v0
	v_mul_lo_u32 v4, v0, v3
	v_sub_u32_e32 v4, v6, v4
	v_add_u32_e32 v5, 1, v0
	v_cmp_ge_u32_e32 vcc, v4, v3
	s_nop 1
	v_cndmask_b32_e32 v0, v0, v5, vcc
	v_sub_u32_e32 v5, v4, v3
	v_cndmask_b32_e32 v4, v4, v5, vcc
	v_add_u32_e32 v5, 1, v0
	v_cmp_ge_u32_e32 vcc, v4, v3
	v_add_u32_e32 v4, 1, v6
	s_nop 0
	v_cndmask_b32_e32 v0, v0, v5, vcc
	v_mul_lo_u32 v5, v3, v0
	v_add_u32_e32 v3, v5, v3
	v_cmp_ne_u32_e32 vcc, v4, v3
	s_and_saveexec_b64 s[4:5], vcc
	s_xor_b64 s[4:5], exec, s[4:5]
	s_cbranch_execz .LBB0_843
	v_readlane_b32 s8, v254, 63
	v_readlane_b32 s9, v255, 0
	s_waitcnt lgkmcnt(0)
	s_nop 3
	global_load_dword v2, v1, s[8:9] sc1
	s_waitcnt vmcnt(0)
	v_cmp_eq_u32_e32 vcc, v2, v0
	s_and_saveexec_b64 s[8:9], vcc
	s_cbranch_execz .LBB0_842
	s_mov_b32 s20, 1
	s_mov_b64 s[10:11], 0
	s_branch .LBB0_833
